# GEMM prologues (P1, P5, P6): all 14 stage loads (K-tiles 0 and 1) requested at once; the tile-0 wait and barrier moved behind them (vmcnt(2) -> vmcnt(8)); on top of v52
# speedup vs baseline: 1.0063x; 1.0031x over previous
; #define PG8_STAGE(bufoff, gbase, voff) do { _Pragma("unroll") for (int _i = 0; _i < 2; ++_i) \
;         __builtin_amdgcn_global_load_lds((const unsigned*)((const char*)(gbase) + (voff)[_i]), (PG8_LAS unsigned*)(lds + (bufoff) + ldsw + _i * 8192), 16, 0, 0); } while (0)
; #define PG8_WAIT_V(n) asm volatile("s_waitcnt vmcnt(" #n ")" ::: "memory")
; #define PG8_BAR __builtin_amdgcn_s_barrier()
; template <class Epi, class Sched, bool ALIGN_EPI = false, bool SP2 = false>
; __device__ __forceinline__ void gemm_phase(PG8_LAS unsigned char* lds, const Gemm g, const Sched& S, const Epi& E, int wid_in) {
;     ...
;     const int lane = lane_o, wid = wid_in, tid = wid * 64 + lane,     wr = wid >> 2, wc = wid & 3, fr = lane & 15, fq = lane >> 4;
;     const int K = g.K, nt = K / BK;
;     unsigned voffA[2], voffB[2];
; #pragma unroll
;     for (int i = 0; i < 2; ++i) { int R, C; stage_rc(tid * 16 + i * 8192, R, C); const int Rb = Epi::PERM ? ((R & ~31) + perm32(R & 31)) : R;
;         voffA[i] = (unsigned)(R * K + C) * 2u; voffB[i] = (unsigned)(Rb * K + C) * 2u; }
;     const size_t kstep = (size_t)(BK * 2);
;     const size_t hstep = (size_t)HALF * K * 2;
;     const size_t tstep = 2 * hstep;
;     const unsigned ldsw = (unsigned)wid * 1024u;
;     const int aoff = lds_byte(wr * 64 + fr, fq * 8), boff = lds_byte(wc * 32 + fr, fq * 8);
;     ...
;     const char* cA = (const char*)g.A + (size_t)cur.pm * tstep; const char* cB = (const char*)g.Bt + (size_t)cur.pn * tstep;
;     S.a_ready(cur);
;     if constexpr (SP2) {
;         PG8_STAGE(PG8_SB(0, 0), cB, voffB); PG8_STAGE(PG8_SB(0, 1), cB + hstep, voffB); PG8_STAGE(PG8_SA(0, 0), cA, voffA); PG8_STAGE(PG8_SA(0, 1), cA + hstep, voffA);
;         if (wr == 1) PG8_BAR;
;         PG8_WAIT_V(2); PG8_BAR;
;         PG8_STAGE(PG8_SB(1, 0), cB + kstep, voffB); PG8_STAGE(PG8_SA(1, 0), cA + kstep, voffA); PG8_STAGE(PG8_SB(1, 1), cB + hstep + kstep, voffB);
;         PG8_WAIT_V(6); PG8_BAR;
.LBB0_221:
	s_add_u32 s14, s96, 0x3c00000
	s_addc_u32 s15, s97, 0
	s_add_u32 s16, s96, 0x5c00000
	s_addc_u32 s17, s97, 0
	s_add_u32 s20, s96, 0x8c00000
	s_addc_u32 s21, s97, 0
	s_add_u32 s22, s96, 0xcc00000
	s_addc_u32 s23, s97, 0
	s_add_u32 s64, s96, 0xd400000
	s_addc_u32 s65, s97, 0
	s_add_u32 s72, s96, 0xdc00000
	s_mov_b64 s[74:75], 0x80
	v_writelane_b32 v252, s64, 16
	s_addc_u32 s73, s97, 0
	s_bfe_u32 s1, s71, 0x20006
	s_add_i32 m0, s34, 0x18000
	v_lshl_add_u64 v[6:7], v[6:7], 0, s[74:75]
	v_writelane_b32 v252, s65, 17
	s_lshl_b32 s3, s1, 5
	global_load_lds_dwordx4 v[6:7], off
	v_lshl_add_u64 v[4:5], v[4:5], 0, s[74:75]
	s_add_i32 m0, s34, 0x1a000
	s_add_i32 s64, s34, 0x8000
	s_add_i32 s65, s34, 0xa000
	global_load_lds_dwordx4 v[4:5], off
	v_lshl_add_u64 v[0:1], v[0:1], 0, s[74:75]
	s_mov_b32 m0, s64
	s_add_u32 s70, s88, 0x40080
	global_load_lds_dwordx4 v[0:1], off
	v_lshl_add_u64 v[0:1], v[2:3], 0, s[74:75]
	s_mov_b32 m0, s65
	s_mov_b32 s5, s71
	s_addc_u32 s71, s89, 0
	global_load_lds_dwordx4 v[0:1], off
	s_add_i32 m0, s34, 0x1c000
	v_lshl_add_u64 v[0:1], s[70:71], 0, v[138:139]
	global_load_lds_dwordx4 v[0:1], off
	v_lshl_add_u64 v[0:1], s[70:71], 0, v[142:143]
	s_add_i32 m0, s34, 0x1e000
	v_and_b32_e32 v2, 48, v8
	global_load_lds_dwordx4 v[0:1], off
	s_waitcnt vmcnt(8)
	s_barrier
	v_and_b32_e32 v0, 15, v8
	v_lshl_or_b32 v168, s0, 6, v0
	v_and_b32_e32 v3, 0xfffffc00, v13
	v_lshl_or_b32 v0, v0, 6, v2
	v_lshlrev_b32_e32 v2, 2, v8
	v_ashrrev_i32_e32 v1, 4, v8
	v_lshl_add_u32 v4, s0, 13, v3
	v_and_b32_e32 v2, 32, v2
	v_lshl_add_u32 v3, s1, 12, v3
	s_cmpk_lt_u32 s5, 0x100
	v_bitop3_b32 v4, v0, v4, v2 bitop3:0xde
	v_bitop3_b32 v169, v0, v3, v2 bitop3:0xde
	s_cselect_b64 s[76:77], -1, 0
	s_bitcmp0_b32 s5, 6
	v_lshlrev_b32_e32 v0, 2, v1
	s_cselect_b64 s[0:1], -1, 0
	v_cmp_gt_i32_e32 vcc, 2, v1
	v_lshl_add_u32 v170, v1, 3, s3
	v_ashrrev_i32_e32 v1, 31, v0
	s_and_b64 s[78:79], s[0:1], vcc
	s_mov_b64 s[0:1], s[96:97]
	v_lshlrev_b64 v[0:1], 2, v[0:1]
	v_lshl_add_u64 v[0:1], s[0:1], 0, v[0:1]
	s_mov_b64 s[0:1], 0x100000
	v_lshl_add_u64 v[146:147], v[0:1], 0, s[0:1]
	s_mov_b64 s[0:1], 0x140000
	v_lshl_add_u64 v[148:149], v[0:1], 0, s[0:1]
	v_lshlrev_b32_e32 v0, 14, v9
	v_and_b32_e32 v0, 0xffff8000, v0
	v_lshl_add_u32 v0, v10, 11, v0
	v_and_b32_e32 v1, 1, v9
	v_lshl_or_b32 v0, v1, 6, v0
	v_lshl_add_u32 v150, v11, 1, v0
	v_lshlrev_b32_e32 v0, 14, v12
	v_and_b32_e32 v0, 0xffff8000, v0
	s_waitcnt vmcnt(6)
	v_readlane_b32 s3, v252, 2
	v_lshl_add_u32 v0, v14, 11, v0
	v_and_b32_e32 v1, 1, v12
	s_ashr_i32 s96, s3, 31
	v_readlane_b32 s3, v252, 3
	v_lshl_or_b32 v0, v1, 6, v0
	s_add_i32 s70, 0, 0x10000
	s_add_i32 s71, 0, 0x14000
	s_ashr_i32 s97, s3, 31
	v_mov_b32_e32 v151, v145
	v_lshl_add_u32 v152, v15, 1, v0
	v_mov_b32_e32 v153, v145
	v_mov_b64_e32 v[154:155], 0x500
	v_mov_b64_e32 v[156:157], 0x4ff
	v_add_u32_e32 v171, s70, v169
	v_add_u32_e32 v172, s71, v169
	v_add_u32_e32 v173, 0, v4
	s_barrier
	s_branch .LBB0_224

; #define PG8_STAGE(bufoff, gbase, voff) do { _Pragma("unroll") for (int _i = 0; _i < 2; ++_i) \
;         __builtin_amdgcn_global_load_lds((const unsigned*)((const char*)(gbase) + (voff)[_i]), (PG8_LAS unsigned*)(lds + (bufoff) + ldsw + _i * 8192), 16, 0, 0); } while (0)
; #define PG8_WAIT_V(n) asm volatile("s_waitcnt vmcnt(" #n ")" ::: "memory")
; #define PG8_BAR __builtin_amdgcn_s_barrier()
; template <int ROT, class Epi0, class Epi1, class Late, class Post0>
; __device__ __forceinline__ void gemm_phase_pair(PG8_LAS unsigned char* lds, const Gemm g0, const Gemm g1, const Unit u, const Epi0& E0, const Epi1& E1, int wid_in, const Late& late, const Post0& post0) {
;     ...
;     const int aoff = lds_byte(wr * 64 + fr, fq * 8), boff = lds_byte(wc * 32 + fr, fq * 8);
;     f32x4 acc[2][2][4][2];
; #pragma unroll
;     for (int a = 0; a < 2; ++a)
; #pragma unroll
;         for (int b = 0; b < 2; ++b)
; #pragma unroll
;             for (int m = 0; m < 4; ++m)
; #pragma unroll
;                 for (int n = 0; n < 2; ++n) acc[a][b][m][n] = (f32x4){0.f, 0.f, 0.f, 0.f};
;     bf16x8 At[4][2], B0[2][2], B1[2][2];
;     const char* cA = (const char*)g0.A + (size_t)u.pm * 2 * hs0; const char* cB = (const char*)g0.Bt + (size_t)u.pn * 2 * hs0;
;     const char* nA = (const char*)g1.A + (size_t)u.pm * 2 * hs1; const char* nB = (const char*)g1.Bt + (size_t)u.pn * 2 * hs1;
;     ...
;     PG8_STAGE(PG8_SB(0, 0), cB + PG8_KT(0), vB0); PG8_STAGE(PG8_SB(0, 1), cB + hs0 + PG8_KT(0), vB0); PG8_STAGE(PG8_SA(0, 0), cA + PG8_KT(0), vA0); PG8_STAGE(PG8_SA(0, 1), cA + hs0 + PG8_KT(0), vA0);
;     if (wr == 1) PG8_BAR;
;     PG8_WAIT_V(2); PG8_BAR;
;     PG8_STAGE(PG8_SB(1, 0), cB + PG8_KT(1), vB0); PG8_STAGE(PG8_SA(1, 0), cA + PG8_KT(1), vA0); PG8_STAGE(PG8_SB(1, 1), cB + hs0 + PG8_KT(1), vB0);
;     PG8_WAIT_V(6); PG8_BAR;
.LBB0_846:
	v_readlane_b32 s7, v252, 5
	s_lshl_b32 s7, s7, 5
	s_and_b32 s52, s7, 0x60
	s_lshl_b32 s12, s6, 6
	v_ashrrev_i32_e32 v1, 6, v143
	s_lshr_b32 s7, s52, 3
	s_lshl_b32 s6, s6, 13
	v_lshl_add_u32 v12, v1, 10, s6
	v_add_lshl_u32 v1, v1, s7, 10
	s_mov_b64 s[6:7], 0x880
	s_add_i32 m0, s40, 0x18000
	v_lshl_add_u64 v[2:3], v[2:3], 0, s[6:7]
	global_load_lds_dwordx4 v[2:3], off
	v_lshl_add_u64 v[2:3], v[4:5], 0, s[6:7]
	s_add_i32 m0, s40, 0x1a000
	s_add_i32 s13, s40, 0x8000
	s_add_i32 s33, s40, 0xa000
	global_load_lds_dwordx4 v[2:3], off
	v_lshl_add_u64 v[2:3], v[6:7], 0, s[6:7]
	s_mov_b32 m0, s13
	s_add_u32 s4, s4, 0x80880
	global_load_lds_dwordx4 v[2:3], off
	v_lshl_add_u64 v[2:3], v[8:9], 0, s[6:7]
	s_mov_b32 m0, s33
	s_addc_u32 s5, s5, 0
	global_load_lds_dwordx4 v[2:3], off
	s_add_i32 m0, s40, 0x1c000
	v_lshl_add_u64 v[2:3], s[4:5], 0, v[132:133]
	global_load_lds_dwordx4 v[2:3], off
	v_lshl_add_u64 v[2:3], s[4:5], 0, v[130:131]
	s_add_i32 m0, s40, 0x1e000
	v_and_b32_e32 v136, 15, v143
	global_load_lds_dwordx4 v[2:3], off
	s_waitcnt vmcnt(8)
	s_barrier
	v_and_b32_e32 v10, 48, v143
	v_lshlrev_b32_e32 v11, 2, v143
	v_lshl_or_b32 v10, v136, 6, v10
	v_and_b32_e32 v11, 32, v11
	v_bitop3_b32 v1, v10, v1, v11 bitop3:0xde
	s_waitcnt vmcnt(6)
	s_add_i32 s49, 0, 0x10000
	s_add_i32 s48, 0, 0x14000
	s_add_i32 s44, 0, 0x18000
	s_add_i32 s43, 0, 0x1c000
	v_bitop3_b32 v10, v10, v12, v11 bitop3:0xde
	v_add_u32_e32 v141, s49, v1
	v_add_u32_e32 v140, s48, v1
	s_add_i32 s49, s49, s36
	s_add_i32 s48, s48, s36
	v_add_u32_e32 v139, s44, v1
	v_add_u32_e32 v138, s43, v1
	s_add_i32 s44, s44, s36
	s_add_i32 s43, s43, s36
	v_or_b32_e32 v142, s12, v136
	v_add_u32_e32 v137, 0, v10
	s_mov_b32 s53, -2
	s_mov_b64 s[4:5], 0x8c80880
	s_add_i32 s51, s40, 0xc000
	s_add_i32 s50, s40, 0xe000
	s_mov_b64 s[6:7], 0xd00900
	s_add_i32 s47, s49, 0x2000
	s_mov_b64 s[10:11], 0xd80900
	s_add_i32 s46, s48, 0x2000
	s_mov_b64 s[24:25], 0x8c00900
	s_mov_b64 s[26:27], 0x8c80900
	s_mov_b64 s[28:29], 0xd00980
	s_add_i32 s42, s44, 0x2000
	s_mov_b64 s[30:31], 0xd80980
	s_add_i32 s41, s43, 0x2000
	s_mov_b64 s[36:37], 0x8c00980
	s_mov_b64 s[38:39], s[96:97]
	v_mov_b32_e32 v134, v130
	v_mov_b32_e32 v130, v0
	v_mov_b32_e32 v0, v131
	v_mov_b32_e32 v1, v131
	v_mov_b32_e32 v2, v131
	v_mov_b32_e32 v3, v131
	v_mov_b32_e32 v4, v131
	v_mov_b32_e32 v5, v131
	v_mov_b32_e32 v6, v131
	v_mov_b32_e32 v7, v131
	v_mov_b32_e32 v8, v131
	v_mov_b32_e32 v9, v131
	v_mov_b32_e32 v10, v131
	v_mov_b32_e32 v11, v131
	v_mov_b32_e32 v12, v131
	v_mov_b32_e32 v13, v131
	v_mov_b32_e32 v14, v131
	v_mov_b32_e32 v15, v131
	v_mov_b32_e32 v16, v131
	v_mov_b32_e32 v17, v131
	v_mov_b32_e32 v18, v131
	v_mov_b32_e32 v19, v131
	v_mov_b32_e32 v20, v131
	v_mov_b32_e32 v21, v131
	v_mov_b32_e32 v22, v131
	v_mov_b32_e32 v23, v131
	v_mov_b32_e32 v24, v131
	v_mov_b32_e32 v25, v131
	v_mov_b32_e32 v26, v131
	v_mov_b32_e32 v27, v131
	v_mov_b32_e32 v28, v131
	v_mov_b32_e32 v29, v131
	v_mov_b32_e32 v30, v131
	v_mov_b32_e32 v31, v131
	v_mov_b32_e32 v32, v131
	v_mov_b32_e32 v33, v131
	v_mov_b32_e32 v34, v131
	v_mov_b32_e32 v35, v131
	v_mov_b32_e32 v36, v131
	v_mov_b32_e32 v37, v131
	v_mov_b32_e32 v38, v131
	v_mov_b32_e32 v39, v131
	v_mov_b32_e32 v40, v131
	v_mov_b32_e32 v41, v131
	v_mov_b32_e32 v42, v131
	v_mov_b32_e32 v43, v131
	v_mov_b32_e32 v44, v131
	v_mov_b32_e32 v45, v131
	v_mov_b32_e32 v46, v131
	v_mov_b32_e32 v47, v131
	v_mov_b32_e32 v48, v131
	v_mov_b32_e32 v49, v131
	v_mov_b32_e32 v50, v131
	v_mov_b32_e32 v51, v131
	v_mov_b32_e32 v52, v131
	v_mov_b32_e32 v53, v131
	v_mov_b32_e32 v54, v131
	v_mov_b32_e32 v55, v131
	v_mov_b32_e32 v56, v131
	v_mov_b32_e32 v57, v131
	v_mov_b32_e32 v58, v131
	v_mov_b32_e32 v59, v131
	v_mov_b32_e32 v60, v131
	v_mov_b32_e32 v61, v131
	v_mov_b32_e32 v62, v131
	v_mov_b32_e32 v63, v131
	v_mov_b32_e32 v64, v131
	v_mov_b32_e32 v65, v131
	v_mov_b32_e32 v66, v131
	v_mov_b32_e32 v67, v131
	v_mov_b32_e32 v68, v131
	v_mov_b32_e32 v69, v131
	v_mov_b32_e32 v70, v131
	v_mov_b32_e32 v71, v131
	v_mov_b32_e32 v72, v131
	v_mov_b32_e32 v73, v131
	v_mov_b32_e32 v74, v131
	v_mov_b32_e32 v75, v131
	v_mov_b32_e32 v76, v131
	v_mov_b32_e32 v77, v131
	v_mov_b32_e32 v78, v131
	v_mov_b32_e32 v79, v131
	v_mov_b32_e32 v80, v131
	v_mov_b32_e32 v81, v131
	v_mov_b32_e32 v82, v131
	v_mov_b32_e32 v83, v131
	v_mov_b32_e32 v84, v131
	v_mov_b32_e32 v85, v131
	v_mov_b32_e32 v86, v131
	v_mov_b32_e32 v87, v131
	v_mov_b32_e32 v88, v131
	v_mov_b32_e32 v89, v131
	v_mov_b32_e32 v90, v131
	v_mov_b32_e32 v91, v131
	v_mov_b32_e32 v92, v131
	v_mov_b32_e32 v93, v131
	v_mov_b32_e32 v94, v131
	v_mov_b32_e32 v95, v131
	v_mov_b32_e32 v96, v131
	v_mov_b32_e32 v97, v131
	v_mov_b32_e32 v98, v131
	v_mov_b32_e32 v99, v131
	v_mov_b32_e32 v100, v131
	v_mov_b32_e32 v101, v131
	v_mov_b32_e32 v102, v131
	v_mov_b32_e32 v103, v131
	v_mov_b32_e32 v104, v131
	v_mov_b32_e32 v105, v131
	v_mov_b32_e32 v106, v131
	v_mov_b32_e32 v107, v131
	v_mov_b32_e32 v108, v131
	v_mov_b32_e32 v109, v131
	v_mov_b32_e32 v110, v131
	v_mov_b32_e32 v111, v131
	v_mov_b32_e32 v112, v131
	v_mov_b32_e32 v113, v131
	v_mov_b32_e32 v114, v131
	v_mov_b32_e32 v115, v131
	v_mov_b32_e32 v116, v131
	v_mov_b32_e32 v117, v131
	v_mov_b32_e32 v118, v131
	v_mov_b32_e32 v119, v131
	v_mov_b32_e32 v120, v131
	v_mov_b32_e32 v121, v131
	v_mov_b32_e32 v122, v131
	v_mov_b32_e32 v123, v131
	v_mov_b32_e32 v124, v131
	v_mov_b32_e32 v125, v131
	v_mov_b32_e32 v126, v131
	v_mov_b32_e32 v127, v131
	s_barrier
	.p2align	6

; #define PG8_STAGE(bufoff, gbase, voff) do { _Pragma("unroll") for (int _i = 0; _i < 2; ++_i) \
;         __builtin_amdgcn_global_load_lds((const unsigned*)((const char*)(gbase) + (voff)[_i]), (PG8_LAS unsigned*)(lds + (bufoff) + ldsw + _i * 8192), 16, 0, 0); } while (0)
; #define PG8_WAIT_V(n) asm volatile("s_waitcnt vmcnt(" #n ")" ::: "memory")
; #define PG8_BAR __builtin_amdgcn_s_barrier()
; template <class Epi, class Sched, bool ALIGN_EPI = false, bool SP2 = false>
; __device__ __forceinline__ void gemm_phase(PG8_LAS unsigned char* lds, const Gemm g, const Sched& S, const Epi& E, int wid_in) {
;     ...
;     if (!S.next(0, cur)) return;
;     f32x4 acc[2][2][4][2];
; #pragma unroll
;     for (int a = 0; a < 2; ++a)
; #pragma unroll
;         for (int b = 0; b < 2; ++b)
; #pragma unroll
;             for (int m = 0; m < 4; ++m)
; #pragma unroll
;                 for (int n = 0; n < 2; ++n) acc[a][b][m][n] = (f32x4){0.f, 0.f, 0.f, 0.f};
;     bf16x8 At[4][2], B0[2][2], B1[2][2];
;     const char* cA = (const char*)g.A + (size_t)cur.pm * tstep; const char* cB = (const char*)g.Bt + (size_t)cur.pn * tstep;
;     S.a_ready(cur);
;     if constexpr (SP2) {
;         PG8_STAGE(PG8_SB(0, 0), cB, voffB); PG8_STAGE(PG8_SB(0, 1), cB + hstep, voffB); PG8_STAGE(PG8_SA(0, 0), cA, voffA); PG8_STAGE(PG8_SA(0, 1), cA + hstep, voffA);
;         if (wr == 1) PG8_BAR;
;         PG8_WAIT_V(2); PG8_BAR;
;         PG8_STAGE(PG8_SB(1, 0), cB + kstep, voffB); PG8_STAGE(PG8_SA(1, 0), cA + kstep, voffA); PG8_STAGE(PG8_SB(1, 1), cB + hstep + kstep, voffB);
;         PG8_WAIT_V(6); PG8_BAR;
.LBB0_976:
	s_mov_b64 s[14:15], 0x80
	s_add_i32 m0, s36, 0x18000
	v_lshl_add_u64 v[6:7], v[6:7], 0, s[14:15]
	s_bfe_u32 s5, s71, 0x20006
	s_lshl_b32 s12, s7, 6
	global_load_lds_dwordx4 v[6:7], off
	v_lshl_add_u64 v[4:5], v[4:5], 0, s[14:15]
	s_add_i32 m0, s36, 0x1a000
	s_add_i32 s41, s36, 0x8000
	s_add_i32 s42, s36, 0xa000
	global_load_lds_dwordx4 v[4:5], off
	v_lshl_add_u64 v[2:3], v[2:3], 0, s[14:15]
	s_mov_b32 m0, s41
	s_add_u32 s2, s26, 0x40080
	global_load_lds_dwordx4 v[2:3], off
	v_lshl_add_u64 v[0:1], v[0:1], 0, s[14:15]
	s_mov_b32 m0, s42
	s_addc_u32 s3, s27, 0
	global_load_lds_dwordx4 v[0:1], off
	s_add_i32 m0, s36, 0x1c000
	v_lshl_add_u64 v[0:1], s[2:3], 0, v[130:131]
	global_load_lds_dwordx4 v[0:1], off
	v_lshl_add_u64 v[0:1], s[2:3], 0, v[134:135]
	s_add_i32 m0, s36, 0x1e000
	s_sext_i32_i8 s6, s0
	global_load_lds_dwordx4 v[0:1], off
	s_waitcnt vmcnt(8)
	s_barrier
	v_lshlrev_b32_e32 v0, 14, v8
	v_and_b32_e32 v0, 0xffff8000, v0
	v_lshl_add_u32 v0, v9, 11, v0
	v_and_b32_e32 v1, 1, v8
	v_lshl_or_b32 v0, v1, 6, v0
	s_mov_b64 s[0:1], 0x40080
	v_lshl_add_u32 v0, v10, 1, v0
	v_mov_b32_e32 v1, v131
	v_lshl_add_u64 v[136:137], v[0:1], 0, s[0:1]
	v_lshlrev_b32_e32 v0, 14, v11
	v_and_b32_e32 v0, 0xffff8000, v0
	v_and_b32_e32 v152, 15, v150
	v_and_b32_e32 v14, 48, v150
	v_and_b32_e32 v15, 0xfffffc00, v151
	v_lshlrev_b32_e32 v17, 2, v150
	v_lshl_add_u32 v0, v12, 11, v0
	v_and_b32_e32 v1, 1, v11
	v_lshl_add_u32 v16, s7, 13, v15
	v_lshl_or_b32 v14, v152, 6, v14
	v_and_b32_e32 v17, 32, v17
	s_waitcnt vmcnt(6)
	v_lshl_or_b32 v0, v1, 6, v0
	v_bitop3_b32 v16, v14, v16, v17 bitop3:0xde
	v_lshl_add_u32 v15, s5, 12, v15
	v_lshl_add_u32 v0, v13, 1, v0
	v_mov_b32_e32 v1, v131
	v_or_b32_e32 v149, s12, v152
	v_bitop3_b32 v153, v14, v15, v17 bitop3:0xde
	v_lshl_add_u64 v[138:139], v[0:1], 0, s[0:1]
	v_mov_b64_e32 v[140:141], 0x100
	v_mov_b64_e32 v[142:143], 0xff
	s_add_i32 s43, 0, 0x10000
	s_add_i32 s44, 0, 0x14000
	v_add_u32_e32 v154, 0, v16
	v_mov_b32_e32 v0, v131
	v_mov_b32_e32 v2, v131
	v_mov_b32_e32 v3, v131
	v_mov_b32_e32 v4, v131
	v_mov_b32_e32 v5, v131
	v_mov_b32_e32 v6, v131
	v_mov_b32_e32 v7, v131
	v_mov_b32_e32 v16, v131
	v_mov_b32_e32 v17, v131
	v_mov_b32_e32 v18, v131
	v_mov_b32_e32 v19, v131
	v_mov_b32_e32 v20, v131
	v_mov_b32_e32 v21, v131
	v_mov_b32_e32 v22, v131
	v_mov_b32_e32 v23, v131
	v_mov_b32_e32 v40, v131
	v_mov_b32_e32 v41, v131
	v_mov_b32_e32 v42, v131
	v_mov_b32_e32 v43, v131
	v_mov_b32_e32 v44, v131
	v_mov_b32_e32 v45, v131
	v_mov_b32_e32 v46, v131
	v_mov_b32_e32 v47, v131
	v_mov_b32_e32 v72, v131
	v_mov_b32_e32 v73, v131
	v_mov_b32_e32 v74, v131
	v_mov_b32_e32 v75, v131
	v_mov_b32_e32 v76, v131
	v_mov_b32_e32 v77, v131
	v_mov_b32_e32 v78, v131
	v_mov_b32_e32 v79, v131
	v_mov_b32_e32 v8, v131
	v_mov_b32_e32 v9, v131
	v_mov_b32_e32 v10, v131
	v_mov_b32_e32 v11, v131
	v_mov_b32_e32 v12, v131
	v_mov_b32_e32 v13, v131
	v_mov_b32_e32 v14, v131
	v_mov_b32_e32 v15, v131
	v_mov_b32_e32 v24, v131
	v_mov_b32_e32 v25, v131
	v_mov_b32_e32 v26, v131
	v_mov_b32_e32 v27, v131
	v_mov_b32_e32 v28, v131
	v_mov_b32_e32 v29, v131
	v_mov_b32_e32 v30, v131
	v_mov_b32_e32 v31, v131
	v_mov_b32_e32 v48, v131
	v_mov_b32_e32 v49, v131
	v_mov_b32_e32 v50, v131
	v_mov_b32_e32 v51, v131
	v_mov_b32_e32 v52, v131
	v_mov_b32_e32 v53, v131
	v_mov_b32_e32 v54, v131
	v_mov_b32_e32 v55, v131
	v_mov_b32_e32 v80, v131
	v_mov_b32_e32 v81, v131
	v_mov_b32_e32 v82, v131
	v_mov_b32_e32 v83, v131
	v_mov_b32_e32 v92, v131
	v_mov_b32_e32 v93, v131
	v_mov_b32_e32 v94, v131
	v_mov_b32_e32 v95, v131
	v_mov_b32_e32 v112, v131
	v_mov_b32_e32 v113, v131
	v_mov_b32_e32 v114, v131
	v_mov_b32_e32 v115, v131
	v_mov_b32_e32 v116, v131
	v_mov_b32_e32 v117, v131
	v_mov_b32_e32 v118, v131
	v_mov_b32_e32 v119, v131
	v_mov_b32_e32 v96, v131
	v_mov_b32_e32 v97, v131
	v_mov_b32_e32 v98, v131
	v_mov_b32_e32 v99, v131
	v_mov_b32_e32 v100, v131
	v_mov_b32_e32 v101, v131
	v_mov_b32_e32 v102, v131
	v_mov_b32_e32 v103, v131
	v_mov_b32_e32 v64, v131
	v_mov_b32_e32 v65, v131
	v_mov_b32_e32 v66, v131
	v_mov_b32_e32 v67, v131
	v_mov_b32_e32 v68, v131
	v_mov_b32_e32 v69, v131
	v_mov_b32_e32 v70, v131
	v_mov_b32_e32 v71, v131
	v_mov_b32_e32 v32, v131
	v_mov_b32_e32 v33, v131
	v_mov_b32_e32 v34, v131
	v_mov_b32_e32 v35, v131
	v_mov_b32_e32 v36, v131
	v_mov_b32_e32 v37, v131
	v_mov_b32_e32 v38, v131
	v_mov_b32_e32 v39, v131
	v_mov_b32_e32 v120, v131
	v_mov_b32_e32 v121, v131
	v_mov_b32_e32 v122, v131
	v_mov_b32_e32 v123, v131
	v_mov_b32_e32 v124, v131
	v_mov_b32_e32 v125, v131
	v_mov_b32_e32 v126, v131
	v_mov_b32_e32 v127, v131
	v_mov_b32_e32 v104, v131
	v_mov_b32_e32 v105, v131
	v_mov_b32_e32 v106, v131
	v_mov_b32_e32 v107, v131
	v_mov_b32_e32 v108, v131
	v_mov_b32_e32 v109, v131
	v_mov_b32_e32 v110, v131
	v_mov_b32_e32 v111, v131
	v_mov_b32_e32 v84, v131
	v_mov_b32_e32 v85, v131
	v_mov_b32_e32 v86, v131
	v_mov_b32_e32 v87, v131
	v_mov_b32_e32 v88, v131
	v_mov_b32_e32 v89, v131
	v_mov_b32_e32 v90, v131
	v_mov_b32_e32 v91, v131
	v_mov_b32_e32 v56, v131
	v_mov_b32_e32 v57, v131
	v_mov_b32_e32 v58, v131
	v_mov_b32_e32 v59, v131
	v_mov_b32_e32 v60, v131
	v_mov_b32_e32 v61, v131
	v_mov_b32_e32 v62, v131
	v_mov_b32_e32 v63, v131
	s_barrier
	s_branch .LBB0_979
